# combination 2: LRU output-loop LDS prefetch + permlane reductions + attention prefetch + mix2 prefetch + LRU batch + tail overlap + fused hoist + XCD-local barriers
# speedup vs baseline: 1.0042x; 1.0042x over previous
.LBB0_318:
	v_add_u32_e32 v70, s6, v122
	ds_read_b64 v[66:67], v70
	ds_read_b64 v[68:69], v70 offset:512
	ds_read_b64 v[226:227], v70 offset:1024
	ds_read_b64 v[228:229], v70 offset:1536
	s_addk_i32 s6, 0x800
	s_cmpk_eq_i32 s6, 0x2000
	s_waitcnt lgkmcnt(3)
	v_mul_f32_e32 v71, v96, v66
	v_fmac_f32_e32 v67, v101, v66
	v_cvt_pk_bf16_f32 v66, v71, v67
	global_store_dword v[64:65], v66, off offset:-2048 nt
	s_waitcnt lgkmcnt(2)
	v_mul_f32_e32 v71, v71, v68
	v_fmac_f32_e32 v69, v67, v68
	v_cvt_pk_bf16_f32 v68, v71, v69
	global_store_dword v[64:65], v68, off offset:-1024 nt
	s_waitcnt lgkmcnt(1)
	v_mul_f32_e32 v68, v71, v226
	v_fma_f32 v67, v69, v226, v227
	v_cvt_pk_bf16_f32 v66, v68, v67
	global_store_dword v[64:65], v66, off nt
	s_waitcnt lgkmcnt(0)
	v_mul_f32_e32 v96, v68, v228
	v_fma_f32 v101, v67, v228, v229
	v_cvt_pk_bf16_f32 v66, v96, v101
	global_store_dword v[64:65], v66, off offset:1024 nt
	v_lshl_add_u64 v[64:65], v[64:65], 0, s[14:15]
	s_cbranch_scc0 .LBB0_318
	s_add_i32 s95, s95, 1
	s_cmp_eq_u32 s95, 4
	v_lshl_add_u64 v[98:99], v[98:99], 0, s[16:17]
	s_cbranch_scc0 .LBB0_317
	s_lshl_b32 s6, s18, 6
	s_or_b32 s6, s6, s94
	s_ashr_i32 s7, s6, 31
	s_lshl_b64 s[6:7], s[6:7], 11
	v_lshl_add_u64 v[0:1], v[94:95], 0, s[6:7]
	v_lshl_add_u64 v[0:1], v[0:1], 0, v[80:81]
	v_add_co_u32_e32 v0, vcc, 0x1a000000, v0
	s_add_i32 s3, s3, s20
	s_nop 0
	v_addc_co_u32_e32 v1, vcc, 0, v1, vcc
	v_mov_b32_e32 v97, v101
	s_cmpk_gt_i32 s3, 0x7ff
	global_store_dwordx2 v[0:1], v[96:97], off
	s_cbranch_scc0 .LBB0_314

.LBB0_1055:
	v_add_u32_e32 v70, s8, v122
	ds_read_b64 v[66:67], v70
	ds_read_b64 v[68:69], v70 offset:512
	ds_read_b64 v[226:227], v70 offset:1024
	ds_read_b64 v[228:229], v70 offset:1536
	s_addk_i32 s8, 0x800
	s_cmpk_eq_i32 s8, 0x2000
	s_waitcnt lgkmcnt(3)
	v_mul_f32_e32 v71, v96, v66
	v_fmac_f32_e32 v67, v101, v66
	v_cvt_pk_bf16_f32 v66, v71, v67
	global_store_dword v[64:65], v66, off offset:-2048 nt
	s_waitcnt lgkmcnt(2)
	v_mul_f32_e32 v71, v71, v68
	v_fmac_f32_e32 v69, v67, v68
	v_cvt_pk_bf16_f32 v68, v71, v69
	global_store_dword v[64:65], v68, off offset:-1024 nt
	s_waitcnt lgkmcnt(1)
	v_mul_f32_e32 v68, v71, v226
	v_fma_f32 v67, v69, v226, v227
	v_cvt_pk_bf16_f32 v66, v68, v67
	global_store_dword v[64:65], v66, off nt
	s_waitcnt lgkmcnt(0)
	v_mul_f32_e32 v96, v68, v228
	v_fma_f32 v101, v67, v228, v229
	v_cvt_pk_bf16_f32 v66, v96, v101
	global_store_dword v[64:65], v66, off offset:1024 nt
	v_lshl_add_u64 v[64:65], v[64:65], 0, s[14:15]
	s_cbranch_scc0 .LBB0_1055
	s_add_i32 s95, s95, 1
	s_cmp_eq_u32 s95, 4
	v_lshl_add_u64 v[98:99], v[98:99], 0, s[20:21]
	s_cbranch_scc0 .LBB0_1054
	s_lshl_b32 s8, s22, 6
	s_or_b32 s8, s8, s94
	s_ashr_i32 s9, s8, 31
	s_lshl_b64 s[8:9], s[8:9], 11
	v_lshl_add_u64 v[0:1], v[94:95], 0, s[8:9]
	v_lshl_add_u64 v[0:1], v[0:1], 0, v[80:81]
	v_add_co_u32_e32 v0, vcc, 0x1a000000, v0
	s_add_i32 s3, s3, s26
	s_nop 0
	v_addc_co_u32_e32 v1, vcc, 0, v1, vcc
	v_mov_b32_e32 v97, v101
	s_cmpk_gt_i32 s3, 0x7ff
	global_store_dwordx2 v[0:1], v[96:97], off
	s_cbranch_scc0 .LBB0_1051
